# v10 + GLA prep items software-pipelined (next item's weight/k/q/gate loads issued after the token loop), gate vectors single-buffered
# baseline (speedup 1.0000x reference)
.LBB0_777:
	s_cmp_lt_i32 s90, 8
	s_cselect_b64 s[2:3], -1, 0
	s_add_u32 s36, s88, 0x115d000
	s_addc_u32 s37, s89, 0
	s_and_b64 s[18:19], s[2:3], s[0:1]
	s_andn2_b64 vcc, exec, s[18:19]
	s_cbranch_vccnz .LBB0_852
	s_cmpk_gt_i32 s58, 0x47f
	s_cbranch_scc1 .LBB0_851
	s_waitcnt vmcnt(0)
	v_readfirstlane_b32 s32, v0
	v_and_b32_e32 v2, 63, v0
	s_mov_b32 s33, 0xbfb8aa3b
	s_mov_b32 s35, 0x3f317217
	s_lshr_b32 s32, s32, 6
	v_lshlrev_b32_e32 v3, 3, v2
	v_lshlrev_b32_e32 v2, 2, v2
	s_mov_b32 s34, s58
	s_mov_b32 s50, 0
	s_mul_hi_u32 s38, s34, 0x1c71c72
	s_mul_i32 s92, s38, 144
	s_sub_i32 s92, s34, s92
	s_mul_hi_u32 s40, s92, 0x71c71c8
	s_mul_i32 s93, s40, 36
	s_sub_i32 s39, s92, s93
	s_lshl_b32 s92, s38, 8
	s_lshl_b32 s93, s39, 6
	s_add_i32 s92, s92, s93
	s_addk_i32 s92, 0x4000
	s_lshl_b32 s94, s38, 11
	s_add_i32 s94, s94, s93
	s_addk_i32 s94, 0xff00
	s_cmp_lt_u32 s39, 4
	s_cselect_b32 s41, s92, s94
	s_lshl_b32 s92, s32, 3
	s_add_i32 s41, s41, s92
	s_lshl_b32 s95, s40, 8
	s_mul_i32 s92, s41, 0x1800
	s_add_u32 s92, s92, s95
	s_add_u32 s42, s96, s92
	s_addc_u32 s43, s97, 0
	s_lshl_b32 s92, s41, 10
	s_add_u32 s92, s92, s95
	s_add_u32 s44, s88, 0xa27d000
	s_addc_u32 s45, s89, 0
	s_add_u32 s44, s44, s92
	s_addc_u32 s45, s45, 0
	s_add_u32 s46, s44, 0x1000000
	s_addc_u32 s47, s45, 0
	s_lshl_b32 s92, s41, 7
	s_add_u32 s48, s88, 0xf1d000
	s_addc_u32 s49, s89, 0
	s_add_u32 s48, s48, s92
	s_addc_u32 s49, s49, 0
	s_lshl_b32 s95, s40, 9
	v_readlane_b32 s52, v251, 18
	v_readlane_b32 s53, v251, 19
	s_nop 3
	s_add_u32 s52, s52, s95
	s_addc_u32 s53, s53, 0
	global_load_dwordx2 v[10:11], v3, s[52:53]
	global_load_dwordx2 v[12:13], v3, s[52:53] offset:2048
	s_add_u32 s52, s52, 0x1000
	s_addc_u32 s53, s53, 0
	global_load_dwordx2 v[14:15], v3, s[52:53]
	global_load_dwordx2 v[16:17], v3, s[52:53] offset:2048
	s_add_u32 s52, s52, 0x1000
	s_addc_u32 s53, s53, 0
	global_load_dwordx2 v[18:19], v3, s[52:53]
	global_load_dwordx2 v[20:21], v3, s[52:53] offset:2048
	s_add_u32 s52, s52, 0x1000
	s_addc_u32 s53, s53, 0
	global_load_dwordx2 v[22:23], v3, s[52:53]
	global_load_dwordx2 v[24:25], v3, s[52:53] offset:2048
	s_add_u32 s52, s52, 0x1000
	s_addc_u32 s53, s53, 0
	global_load_dwordx2 v[26:27], v3, s[52:53]
	global_load_dwordx2 v[28:29], v3, s[52:53] offset:2048
	s_add_u32 s52, s52, 0x1000
	s_addc_u32 s53, s53, 0
	global_load_dwordx2 v[30:31], v3, s[52:53]
	global_load_dwordx2 v[32:33], v3, s[52:53] offset:2048
	s_add_u32 s52, s52, 0x1000
	s_addc_u32 s53, s53, 0
	global_load_dwordx2 v[34:35], v3, s[52:53]
	global_load_dwordx2 v[36:37], v3, s[52:53] offset:2048
	s_add_u32 s52, s52, 0x1000
	s_addc_u32 s53, s53, 0
	global_load_dwordx2 v[38:39], v3, s[52:53]
	global_load_dwordx2 v[40:41], v3, s[52:53] offset:2048
	v_readlane_b32 s52, v251, 24
	v_readlane_b32 s53, v251, 25
	s_nop 3
	s_add_u32 s52, s52, s95
	s_addc_u32 s53, s53, 0
	global_load_dwordx2 v[42:43], v3, s[52:53]
	global_load_dwordx2 v[44:45], v3, s[52:53] offset:2048
	s_add_u32 s52, s52, 0x1000
	s_addc_u32 s53, s53, 0
	global_load_dwordx2 v[46:47], v3, s[52:53]
	global_load_dwordx2 v[48:49], v3, s[52:53] offset:2048
	s_add_u32 s52, s52, 0x1000
	s_addc_u32 s53, s53, 0
	global_load_dwordx2 v[50:51], v3, s[52:53]
	global_load_dwordx2 v[52:53], v3, s[52:53] offset:2048
	s_add_u32 s52, s52, 0x1000
	s_addc_u32 s53, s53, 0
	global_load_dwordx2 v[54:55], v3, s[52:53]
	global_load_dwordx2 v[56:57], v3, s[52:53] offset:2048
	s_add_u32 s52, s52, 0x1000
	s_addc_u32 s53, s53, 0
	global_load_dwordx2 v[58:59], v3, s[52:53]
	global_load_dwordx2 v[60:61], v3, s[52:53] offset:2048
	s_add_u32 s52, s52, 0x1000
	s_addc_u32 s53, s53, 0
	global_load_dwordx2 v[62:63], v3, s[52:53]
	global_load_dwordx2 v[64:65], v3, s[52:53] offset:2048
	s_add_u32 s52, s52, 0x1000
	s_addc_u32 s53, s53, 0
	global_load_dwordx2 v[66:67], v3, s[52:53]
	global_load_dwordx2 v[68:69], v3, s[52:53] offset:2048
	s_add_u32 s52, s52, 0x1000
	s_addc_u32 s53, s53, 0
	global_load_dwordx2 v[70:71], v3, s[52:53]
	global_load_dwordx2 v[72:73], v3, s[52:53] offset:2048
	v_readlane_b32 s52, v251, 20
	v_readlane_b32 s53, v251, 21
	s_nop 3
	s_add_u32 s52, s52, s95
	s_addc_u32 s53, s53, 0
	global_load_dwordx2 v[74:75], v3, s[52:53]
	v_readlane_b32 s52, v251, 26
	v_readlane_b32 s53, v251, 27
	s_nop 3
	s_add_u32 s52, s52, s95
	s_addc_u32 s53, s53, 0
	global_load_dwordx2 v[76:77], v3, s[52:53]
	s_load_dwordx16 s[0:15], s[48:49], 0x0
	s_load_dwordx16 s[64:79], s[48:49], 0x40
	s_mov_b64 s[52:53], s[42:43]
	global_load_dword v200, v2, s[52:53] offset:1024
	s_add_u32 s52, s52, 0x1800
	s_addc_u32 s53, s53, 0
	global_load_dword v201, v2, s[52:53] offset:1024
	s_add_u32 s52, s52, 0x1800
	s_addc_u32 s53, s53, 0
	global_load_dword v202, v2, s[52:53] offset:1024
	s_add_u32 s52, s52, 0x1800
	s_addc_u32 s53, s53, 0
	global_load_dword v203, v2, s[52:53] offset:1024
	s_add_u32 s52, s52, 0x1800
	s_addc_u32 s53, s53, 0
	global_load_dword v204, v2, s[52:53] offset:1024
	s_add_u32 s52, s52, 0x1800
	s_addc_u32 s53, s53, 0
	global_load_dword v205, v2, s[52:53] offset:1024
	s_add_u32 s52, s52, 0x1800
	s_addc_u32 s53, s53, 0
	global_load_dword v206, v2, s[52:53] offset:1024
	s_add_u32 s52, s52, 0x1800
	s_addc_u32 s53, s53, 0
	global_load_dword v207, v2, s[52:53] offset:1024
	s_cmp_lt_u32 s39, 4
	s_cbranch_scc1 .Lp7_noq_load_first
	s_mov_b64 s[52:53], s[42:43]
	global_load_dword v208, v2, s[52:53]
	s_add_u32 s52, s52, 0x1800
	s_addc_u32 s53, s53, 0
	global_load_dword v209, v2, s[52:53]
	s_add_u32 s52, s52, 0x1800
	s_addc_u32 s53, s53, 0
	global_load_dword v210, v2, s[52:53]
	s_add_u32 s52, s52, 0x1800
	s_addc_u32 s53, s53, 0
	global_load_dword v211, v2, s[52:53]
	s_add_u32 s52, s52, 0x1800
	s_addc_u32 s53, s53, 0
	global_load_dword v212, v2, s[52:53]
	s_add_u32 s52, s52, 0x1800
	s_addc_u32 s53, s53, 0
	global_load_dword v213, v2, s[52:53]
	s_add_u32 s52, s52, 0x1800
	s_addc_u32 s53, s53, 0
	global_load_dword v214, v2, s[52:53]
	s_add_u32 s52, s52, 0x1800
	s_addc_u32 s53, s53, 0
	global_load_dword v215, v2, s[52:53]
.Lp7_noq_load_first:
.Lp7_item:
	s_waitcnt vmcnt(0)
	v_mov_b32_e32 v80, v200
	v_mov_b32_e32 v81, v201
	v_mov_b32_e32 v82, v202
	v_mov_b32_e32 v83, v203
	v_mov_b32_e32 v84, v204
	v_mov_b32_e32 v85, v205
	v_mov_b32_e32 v86, v206
	v_mov_b32_e32 v87, v207
	v_mov_b32_e32 v88, v208
	v_mov_b32_e32 v89, v209
	v_mov_b32_e32 v90, v210
	v_mov_b32_e32 v91, v211
	v_mov_b32_e32 v92, v212
	v_mov_b32_e32 v93, v213
	v_mov_b32_e32 v94, v214
	v_mov_b32_e32 v95, v215
	s_waitcnt lgkmcnt(0)
	v_fma_f32 v128, s0, v10, v74
	v_fma_f32 v129, s0, v11, v75
	v_fmac_f32_e32 v128, s1, v12
	v_fmac_f32_e32 v129, s1, v13
	v_fmac_f32_e32 v128, s2, v14
	v_fmac_f32_e32 v129, s2, v15
	v_fmac_f32_e32 v128, s3, v16
	v_fmac_f32_e32 v129, s3, v17
	v_fmac_f32_e32 v128, s4, v18
	v_fmac_f32_e32 v129, s4, v19
	v_fmac_f32_e32 v128, s5, v20
	v_fmac_f32_e32 v129, s5, v21
	v_fmac_f32_e32 v128, s6, v22
	v_fmac_f32_e32 v129, s6, v23
	v_fmac_f32_e32 v128, s7, v24
	v_fmac_f32_e32 v129, s7, v25
	v_fmac_f32_e32 v128, s8, v26
	v_fmac_f32_e32 v129, s8, v27
	v_fmac_f32_e32 v128, s9, v28
	v_fmac_f32_e32 v129, s9, v29
	v_fmac_f32_e32 v128, s10, v30
	v_fmac_f32_e32 v129, s10, v31
	v_fmac_f32_e32 v128, s11, v32
	v_fmac_f32_e32 v129, s11, v33
	v_fmac_f32_e32 v128, s12, v34
	v_fmac_f32_e32 v129, s12, v35
	v_fmac_f32_e32 v128, s13, v36
	v_fmac_f32_e32 v129, s13, v37
	v_fmac_f32_e32 v128, s14, v38
	v_fmac_f32_e32 v129, s14, v39
	v_fmac_f32_e32 v128, s15, v40
	v_fmac_f32_e32 v129, s15, v41
	s_add_u32 s48, s48, 0x80
	s_addc_u32 s49, s49, 0
	s_load_dwordx16 s[0:15], s[48:49], 0x0
	v_fma_f32 v130, s64, v42, v76
	v_fma_f32 v131, s64, v43, v77
	v_fmac_f32_e32 v130, s65, v44
	v_fmac_f32_e32 v131, s65, v45
	v_fmac_f32_e32 v130, s66, v46
	v_fmac_f32_e32 v131, s66, v47
	v_fmac_f32_e32 v130, s67, v48
	v_fmac_f32_e32 v131, s67, v49
	v_fmac_f32_e32 v130, s68, v50
	v_fmac_f32_e32 v131, s68, v51
	v_fmac_f32_e32 v130, s69, v52
	v_fmac_f32_e32 v131, s69, v53
	v_fmac_f32_e32 v130, s70, v54
	v_fmac_f32_e32 v131, s70, v55
	v_fmac_f32_e32 v130, s71, v56
	v_fmac_f32_e32 v131, s71, v57
	v_fmac_f32_e32 v130, s72, v58
	v_fmac_f32_e32 v131, s72, v59
	v_fmac_f32_e32 v130, s73, v60
	v_fmac_f32_e32 v131, s73, v61
	v_fmac_f32_e32 v130, s74, v62
	v_fmac_f32_e32 v131, s74, v63
	v_fmac_f32_e32 v130, s75, v64
	v_fmac_f32_e32 v131, s75, v65
	v_fmac_f32_e32 v130, s76, v66
	v_fmac_f32_e32 v131, s76, v67
	v_fmac_f32_e32 v130, s77, v68
	v_fmac_f32_e32 v131, s77, v69
	v_fmac_f32_e32 v130, s78, v70
	v_fmac_f32_e32 v131, s78, v71
	v_fmac_f32_e32 v130, s79, v72
	v_fmac_f32_e32 v131, s79, v73
	s_load_dwordx16 s[64:79], s[48:49], 0x40
	v_mul_f32_e64 v132, |v128|, s33
	v_mul_f32_e64 v133, |v129|, s33
	v_mul_f32_e64 v134, |v130|, s33
	v_mul_f32_e64 v135, |v131|, s33
	v_exp_f32_e32 v132, v132
	v_exp_f32_e32 v133, v133
	v_exp_f32_e32 v134, v134
	v_exp_f32_e32 v135, v135
	v_add_f32_e32 v132, 1.0, v132
	v_add_f32_e32 v133, 1.0, v133
	v_add_f32_e32 v134, 1.0, v134
	v_add_f32_e32 v135, 1.0, v135
	v_log_f32_e32 v136, v132
	v_log_f32_e32 v137, v133
	v_log_f32_e32 v138, v134
	v_log_f32_e32 v139, v135
	v_mul_f32_e32 v140, 0x3f317217, v136
	v_mul_f32_e32 v141, 0x3f317217, v137
	v_mul_f32_e32 v142, 0x3f317217, v138
	v_mul_f32_e32 v143, 0x3f317217, v139
	v_fma_f32 v144, v136, s35, -v140
	v_fma_f32 v145, v137, s35, -v141
	v_fma_f32 v146, v138, s35, -v142
	v_fma_f32 v147, v139, s35, -v143
	v_fmac_f32_e32 v144, 0x3377d1cf, v136
	v_fmac_f32_e32 v145, 0x3377d1cf, v137
	v_fmac_f32_e32 v146, 0x3377d1cf, v138
	v_fmac_f32_e32 v147, 0x3377d1cf, v139
	v_fmac_f32_e32 v144, 0x3f317217, v136
	v_fmac_f32_e32 v145, 0x3f317217, v137
	v_fmac_f32_e32 v146, 0x3f317217, v138
	v_fmac_f32_e32 v147, 0x3f317217, v139
	v_min_f32_e32 v128, 0, v128
	v_min_f32_e32 v129, 0, v129
	v_min_f32_e32 v130, 0, v130
	v_min_f32_e32 v131, 0, v131
	v_sub_f32_e32 v128, v128, v144
	v_sub_f32_e32 v129, v129, v145
	v_sub_f32_e32 v130, v130, v146
	v_sub_f32_e32 v131, v131, v147
	v_mul_f32_e32 v96, 0x3d800000, v128
	v_mul_f32_e32 v97, 0x3d800000, v129
	v_mul_f32_e32 v112, 0x3d800000, v130
	v_mul_f32_e32 v113, 0x3d800000, v131
	s_waitcnt lgkmcnt(0)
	v_fma_f32 v128, s0, v10, v74
	v_fma_f32 v129, s0, v11, v75
	v_fmac_f32_e32 v128, s1, v12
	v_fmac_f32_e32 v129, s1, v13
	v_fmac_f32_e32 v128, s2, v14
	v_fmac_f32_e32 v129, s2, v15
	v_fmac_f32_e32 v128, s3, v16
	v_fmac_f32_e32 v129, s3, v17
	v_fmac_f32_e32 v128, s4, v18
	v_fmac_f32_e32 v129, s4, v19
	v_fmac_f32_e32 v128, s5, v20
	v_fmac_f32_e32 v129, s5, v21
	v_fmac_f32_e32 v128, s6, v22
	v_fmac_f32_e32 v129, s6, v23
	v_fmac_f32_e32 v128, s7, v24
	v_fmac_f32_e32 v129, s7, v25
	v_fmac_f32_e32 v128, s8, v26
	v_fmac_f32_e32 v129, s8, v27
	v_fmac_f32_e32 v128, s9, v28
	v_fmac_f32_e32 v129, s9, v29
	v_fmac_f32_e32 v128, s10, v30
	v_fmac_f32_e32 v129, s10, v31
	v_fmac_f32_e32 v128, s11, v32
	v_fmac_f32_e32 v129, s11, v33
	v_fmac_f32_e32 v128, s12, v34
	v_fmac_f32_e32 v129, s12, v35
	v_fmac_f32_e32 v128, s13, v36
	v_fmac_f32_e32 v129, s13, v37
	v_fmac_f32_e32 v128, s14, v38
	v_fmac_f32_e32 v129, s14, v39
	v_fmac_f32_e32 v128, s15, v40
	v_fmac_f32_e32 v129, s15, v41
	s_add_u32 s48, s48, 0x80
	s_addc_u32 s49, s49, 0
	s_load_dwordx16 s[0:15], s[48:49], 0x0
	v_fma_f32 v130, s64, v42, v76
	v_fma_f32 v131, s64, v43, v77
	v_fmac_f32_e32 v130, s65, v44
	v_fmac_f32_e32 v131, s65, v45
	v_fmac_f32_e32 v130, s66, v46
	v_fmac_f32_e32 v131, s66, v47
	v_fmac_f32_e32 v130, s67, v48
	v_fmac_f32_e32 v131, s67, v49
	v_fmac_f32_e32 v130, s68, v50
	v_fmac_f32_e32 v131, s68, v51
	v_fmac_f32_e32 v130, s69, v52
	v_fmac_f32_e32 v131, s69, v53
	v_fmac_f32_e32 v130, s70, v54
	v_fmac_f32_e32 v131, s70, v55
	v_fmac_f32_e32 v130, s71, v56
	v_fmac_f32_e32 v131, s71, v57
	v_fmac_f32_e32 v130, s72, v58
	v_fmac_f32_e32 v131, s72, v59
	v_fmac_f32_e32 v130, s73, v60
	v_fmac_f32_e32 v131, s73, v61
	v_fmac_f32_e32 v130, s74, v62
	v_fmac_f32_e32 v131, s74, v63
	v_fmac_f32_e32 v130, s75, v64
	v_fmac_f32_e32 v131, s75, v65
	v_fmac_f32_e32 v130, s76, v66
	v_fmac_f32_e32 v131, s76, v67
	v_fmac_f32_e32 v130, s77, v68
	v_fmac_f32_e32 v131, s77, v69
	v_fmac_f32_e32 v130, s78, v70
	v_fmac_f32_e32 v131, s78, v71
	v_fmac_f32_e32 v130, s79, v72
	v_fmac_f32_e32 v131, s79, v73
	s_load_dwordx16 s[64:79], s[48:49], 0x40
	v_mul_f32_e64 v132, |v128|, s33
	v_mul_f32_e64 v133, |v129|, s33
	v_mul_f32_e64 v134, |v130|, s33
	v_mul_f32_e64 v135, |v131|, s33
	v_exp_f32_e32 v132, v132
	v_exp_f32_e32 v133, v133
	v_exp_f32_e32 v134, v134
	v_exp_f32_e32 v135, v135
	v_add_f32_e32 v132, 1.0, v132
	v_add_f32_e32 v133, 1.0, v133
	v_add_f32_e32 v134, 1.0, v134
	v_add_f32_e32 v135, 1.0, v135
	v_log_f32_e32 v136, v132
	v_log_f32_e32 v137, v133
	v_log_f32_e32 v138, v134
	v_log_f32_e32 v139, v135
	v_mul_f32_e32 v140, 0x3f317217, v136
	v_mul_f32_e32 v141, 0x3f317217, v137
	v_mul_f32_e32 v142, 0x3f317217, v138
	v_mul_f32_e32 v143, 0x3f317217, v139
	v_fma_f32 v144, v136, s35, -v140
	v_fma_f32 v145, v137, s35, -v141
	v_fma_f32 v146, v138, s35, -v142
	v_fma_f32 v147, v139, s35, -v143
	v_fmac_f32_e32 v144, 0x3377d1cf, v136
	v_fmac_f32_e32 v145, 0x3377d1cf, v137
	v_fmac_f32_e32 v146, 0x3377d1cf, v138
	v_fmac_f32_e32 v147, 0x3377d1cf, v139
	v_fmac_f32_e32 v144, 0x3f317217, v136
	v_fmac_f32_e32 v145, 0x3f317217, v137
	v_fmac_f32_e32 v146, 0x3f317217, v138
	v_fmac_f32_e32 v147, 0x3f317217, v139
	v_min_f32_e32 v128, 0, v128
	v_min_f32_e32 v129, 0, v129
	v_min_f32_e32 v130, 0, v130
	v_min_f32_e32 v131, 0, v131
	v_sub_f32_e32 v128, v128, v144
	v_sub_f32_e32 v129, v129, v145
	v_sub_f32_e32 v130, v130, v146
	v_sub_f32_e32 v131, v131, v147
	v_mul_f32_e32 v98, 0x3d800000, v128
	v_mul_f32_e32 v99, 0x3d800000, v129
	v_mul_f32_e32 v114, 0x3d800000, v130
	v_mul_f32_e32 v115, 0x3d800000, v131
	s_waitcnt lgkmcnt(0)
	v_fma_f32 v128, s0, v10, v74
	v_fma_f32 v129, s0, v11, v75
	v_fmac_f32_e32 v128, s1, v12
	v_fmac_f32_e32 v129, s1, v13
	v_fmac_f32_e32 v128, s2, v14
	v_fmac_f32_e32 v129, s2, v15
	v_fmac_f32_e32 v128, s3, v16
	v_fmac_f32_e32 v129, s3, v17
	v_fmac_f32_e32 v128, s4, v18
	v_fmac_f32_e32 v129, s4, v19
	v_fmac_f32_e32 v128, s5, v20
	v_fmac_f32_e32 v129, s5, v21
	v_fmac_f32_e32 v128, s6, v22
	v_fmac_f32_e32 v129, s6, v23
	v_fmac_f32_e32 v128, s7, v24
	v_fmac_f32_e32 v129, s7, v25
	v_fmac_f32_e32 v128, s8, v26
	v_fmac_f32_e32 v129, s8, v27
	v_fmac_f32_e32 v128, s9, v28
	v_fmac_f32_e32 v129, s9, v29
	v_fmac_f32_e32 v128, s10, v30
	v_fmac_f32_e32 v129, s10, v31
	v_fmac_f32_e32 v128, s11, v32
	v_fmac_f32_e32 v129, s11, v33
	v_fmac_f32_e32 v128, s12, v34
	v_fmac_f32_e32 v129, s12, v35
	v_fmac_f32_e32 v128, s13, v36
	v_fmac_f32_e32 v129, s13, v37
	v_fmac_f32_e32 v128, s14, v38
	v_fmac_f32_e32 v129, s14, v39
	v_fmac_f32_e32 v128, s15, v40
	v_fmac_f32_e32 v129, s15, v41
	s_add_u32 s48, s48, 0x80
	s_addc_u32 s49, s49, 0
	s_load_dwordx16 s[0:15], s[48:49], 0x0
	v_fma_f32 v130, s64, v42, v76
	v_fma_f32 v131, s64, v43, v77
	v_fmac_f32_e32 v130, s65, v44
	v_fmac_f32_e32 v131, s65, v45
	v_fmac_f32_e32 v130, s66, v46
	v_fmac_f32_e32 v131, s66, v47
	v_fmac_f32_e32 v130, s67, v48
	v_fmac_f32_e32 v131, s67, v49
	v_fmac_f32_e32 v130, s68, v50
	v_fmac_f32_e32 v131, s68, v51
	v_fmac_f32_e32 v130, s69, v52
	v_fmac_f32_e32 v131, s69, v53
	v_fmac_f32_e32 v130, s70, v54
	v_fmac_f32_e32 v131, s70, v55
	v_fmac_f32_e32 v130, s71, v56
	v_fmac_f32_e32 v131, s71, v57
	v_fmac_f32_e32 v130, s72, v58
	v_fmac_f32_e32 v131, s72, v59
	v_fmac_f32_e32 v130, s73, v60
	v_fmac_f32_e32 v131, s73, v61
	v_fmac_f32_e32 v130, s74, v62
	v_fmac_f32_e32 v131, s74, v63
	v_fmac_f32_e32 v130, s75, v64
	v_fmac_f32_e32 v131, s75, v65
	v_fmac_f32_e32 v130, s76, v66
	v_fmac_f32_e32 v131, s76, v67
	v_fmac_f32_e32 v130, s77, v68
	v_fmac_f32_e32 v131, s77, v69
	v_fmac_f32_e32 v130, s78, v70
	v_fmac_f32_e32 v131, s78, v71
	v_fmac_f32_e32 v130, s79, v72
	v_fmac_f32_e32 v131, s79, v73
	s_load_dwordx16 s[64:79], s[48:49], 0x40
	v_mul_f32_e64 v132, |v128|, s33
	v_mul_f32_e64 v133, |v129|, s33
	v_mul_f32_e64 v134, |v130|, s33
	v_mul_f32_e64 v135, |v131|, s33
	v_exp_f32_e32 v132, v132
	v_exp_f32_e32 v133, v133
	v_exp_f32_e32 v134, v134
	v_exp_f32_e32 v135, v135
	v_add_f32_e32 v132, 1.0, v132
	v_add_f32_e32 v133, 1.0, v133
	v_add_f32_e32 v134, 1.0, v134
	v_add_f32_e32 v135, 1.0, v135
	v_log_f32_e32 v136, v132
	v_log_f32_e32 v137, v133
	v_log_f32_e32 v138, v134
	v_log_f32_e32 v139, v135
	v_mul_f32_e32 v140, 0x3f317217, v136
	v_mul_f32_e32 v141, 0x3f317217, v137
	v_mul_f32_e32 v142, 0x3f317217, v138
	v_mul_f32_e32 v143, 0x3f317217, v139
	v_fma_f32 v144, v136, s35, -v140
	v_fma_f32 v145, v137, s35, -v141
	v_fma_f32 v146, v138, s35, -v142
	v_fma_f32 v147, v139, s35, -v143
	v_fmac_f32_e32 v144, 0x3377d1cf, v136
	v_fmac_f32_e32 v145, 0x3377d1cf, v137
	v_fmac_f32_e32 v146, 0x3377d1cf, v138
	v_fmac_f32_e32 v147, 0x3377d1cf, v139
	v_fmac_f32_e32 v144, 0x3f317217, v136
	v_fmac_f32_e32 v145, 0x3f317217, v137
	v_fmac_f32_e32 v146, 0x3f317217, v138
	v_fmac_f32_e32 v147, 0x3f317217, v139
	v_min_f32_e32 v128, 0, v128
	v_min_f32_e32 v129, 0, v129
	v_min_f32_e32 v130, 0, v130
	v_min_f32_e32 v131, 0, v131
	v_sub_f32_e32 v128, v128, v144
	v_sub_f32_e32 v129, v129, v145
	v_sub_f32_e32 v130, v130, v146
	v_sub_f32_e32 v131, v131, v147
	v_mul_f32_e32 v100, 0x3d800000, v128
	v_mul_f32_e32 v101, 0x3d800000, v129
	v_mul_f32_e32 v116, 0x3d800000, v130
	v_mul_f32_e32 v117, 0x3d800000, v131
	s_waitcnt lgkmcnt(0)
	v_fma_f32 v128, s0, v10, v74
	v_fma_f32 v129, s0, v11, v75
	v_fmac_f32_e32 v128, s1, v12
	v_fmac_f32_e32 v129, s1, v13
	v_fmac_f32_e32 v128, s2, v14
	v_fmac_f32_e32 v129, s2, v15
	v_fmac_f32_e32 v128, s3, v16
	v_fmac_f32_e32 v129, s3, v17
	v_fmac_f32_e32 v128, s4, v18
	v_fmac_f32_e32 v129, s4, v19
	v_fmac_f32_e32 v128, s5, v20
	v_fmac_f32_e32 v129, s5, v21
	v_fmac_f32_e32 v128, s6, v22
	v_fmac_f32_e32 v129, s6, v23
	v_fmac_f32_e32 v128, s7, v24
	v_fmac_f32_e32 v129, s7, v25
	v_fmac_f32_e32 v128, s8, v26
	v_fmac_f32_e32 v129, s8, v27
	v_fmac_f32_e32 v128, s9, v28
	v_fmac_f32_e32 v129, s9, v29
	v_fmac_f32_e32 v128, s10, v30
	v_fmac_f32_e32 v129, s10, v31
	v_fmac_f32_e32 v128, s11, v32
	v_fmac_f32_e32 v129, s11, v33
	v_fmac_f32_e32 v128, s12, v34
	v_fmac_f32_e32 v129, s12, v35
	v_fmac_f32_e32 v128, s13, v36
	v_fmac_f32_e32 v129, s13, v37
	v_fmac_f32_e32 v128, s14, v38
	v_fmac_f32_e32 v129, s14, v39
	v_fmac_f32_e32 v128, s15, v40
	v_fmac_f32_e32 v129, s15, v41
	s_add_u32 s48, s48, 0x80
	s_addc_u32 s49, s49, 0
	s_load_dwordx16 s[0:15], s[48:49], 0x0
	v_fma_f32 v130, s64, v42, v76
	v_fma_f32 v131, s64, v43, v77
	v_fmac_f32_e32 v130, s65, v44
	v_fmac_f32_e32 v131, s65, v45
	v_fmac_f32_e32 v130, s66, v46
	v_fmac_f32_e32 v131, s66, v47
	v_fmac_f32_e32 v130, s67, v48
	v_fmac_f32_e32 v131, s67, v49
	v_fmac_f32_e32 v130, s68, v50
	v_fmac_f32_e32 v131, s68, v51
	v_fmac_f32_e32 v130, s69, v52
	v_fmac_f32_e32 v131, s69, v53
	v_fmac_f32_e32 v130, s70, v54
	v_fmac_f32_e32 v131, s70, v55
	v_fmac_f32_e32 v130, s71, v56
	v_fmac_f32_e32 v131, s71, v57
	v_fmac_f32_e32 v130, s72, v58
	v_fmac_f32_e32 v131, s72, v59
	v_fmac_f32_e32 v130, s73, v60
	v_fmac_f32_e32 v131, s73, v61
	v_fmac_f32_e32 v130, s74, v62
	v_fmac_f32_e32 v131, s74, v63
	v_fmac_f32_e32 v130, s75, v64
	v_fmac_f32_e32 v131, s75, v65
	v_fmac_f32_e32 v130, s76, v66
	v_fmac_f32_e32 v131, s76, v67
	v_fmac_f32_e32 v130, s77, v68
	v_fmac_f32_e32 v131, s77, v69
	v_fmac_f32_e32 v130, s78, v70
	v_fmac_f32_e32 v131, s78, v71
	v_fmac_f32_e32 v130, s79, v72
	v_fmac_f32_e32 v131, s79, v73
	s_load_dwordx16 s[64:79], s[48:49], 0x40
	v_mul_f32_e64 v132, |v128|, s33
	v_mul_f32_e64 v133, |v129|, s33
	v_mul_f32_e64 v134, |v130|, s33
	v_mul_f32_e64 v135, |v131|, s33
	v_exp_f32_e32 v132, v132
	v_exp_f32_e32 v133, v133
	v_exp_f32_e32 v134, v134
	v_exp_f32_e32 v135, v135
	v_add_f32_e32 v132, 1.0, v132
	v_add_f32_e32 v133, 1.0, v133
	v_add_f32_e32 v134, 1.0, v134
	v_add_f32_e32 v135, 1.0, v135
	v_log_f32_e32 v136, v132
	v_log_f32_e32 v137, v133
	v_log_f32_e32 v138, v134
	v_log_f32_e32 v139, v135
	v_mul_f32_e32 v140, 0x3f317217, v136
	v_mul_f32_e32 v141, 0x3f317217, v137
	v_mul_f32_e32 v142, 0x3f317217, v138
	v_mul_f32_e32 v143, 0x3f317217, v139
	v_fma_f32 v144, v136, s35, -v140
	v_fma_f32 v145, v137, s35, -v141
	v_fma_f32 v146, v138, s35, -v142
	v_fma_f32 v147, v139, s35, -v143
	v_fmac_f32_e32 v144, 0x3377d1cf, v136
	v_fmac_f32_e32 v145, 0x3377d1cf, v137
	v_fmac_f32_e32 v146, 0x3377d1cf, v138
	v_fmac_f32_e32 v147, 0x3377d1cf, v139
	v_fmac_f32_e32 v144, 0x3f317217, v136
	v_fmac_f32_e32 v145, 0x3f317217, v137
	v_fmac_f32_e32 v146, 0x3f317217, v138
	v_fmac_f32_e32 v147, 0x3f317217, v139
	v_min_f32_e32 v128, 0, v128
	v_min_f32_e32 v129, 0, v129
	v_min_f32_e32 v130, 0, v130
	v_min_f32_e32 v131, 0, v131
	v_sub_f32_e32 v128, v128, v144
	v_sub_f32_e32 v129, v129, v145
	v_sub_f32_e32 v130, v130, v146
	v_sub_f32_e32 v131, v131, v147
	v_mul_f32_e32 v102, 0x3d800000, v128
	v_mul_f32_e32 v103, 0x3d800000, v129
	v_mul_f32_e32 v118, 0x3d800000, v130
	v_mul_f32_e32 v119, 0x3d800000, v131
	s_waitcnt lgkmcnt(0)
	v_fma_f32 v128, s0, v10, v74
	v_fma_f32 v129, s0, v11, v75
	v_fmac_f32_e32 v128, s1, v12
	v_fmac_f32_e32 v129, s1, v13
	v_fmac_f32_e32 v128, s2, v14
	v_fmac_f32_e32 v129, s2, v15
	v_fmac_f32_e32 v128, s3, v16
	v_fmac_f32_e32 v129, s3, v17
	v_fmac_f32_e32 v128, s4, v18
	v_fmac_f32_e32 v129, s4, v19
	v_fmac_f32_e32 v128, s5, v20
	v_fmac_f32_e32 v129, s5, v21
	v_fmac_f32_e32 v128, s6, v22
	v_fmac_f32_e32 v129, s6, v23
	v_fmac_f32_e32 v128, s7, v24
	v_fmac_f32_e32 v129, s7, v25
	v_fmac_f32_e32 v128, s8, v26
	v_fmac_f32_e32 v129, s8, v27
	v_fmac_f32_e32 v128, s9, v28
	v_fmac_f32_e32 v129, s9, v29
	v_fmac_f32_e32 v128, s10, v30
	v_fmac_f32_e32 v129, s10, v31
	v_fmac_f32_e32 v128, s11, v32
	v_fmac_f32_e32 v129, s11, v33
	v_fmac_f32_e32 v128, s12, v34
	v_fmac_f32_e32 v129, s12, v35
	v_fmac_f32_e32 v128, s13, v36
	v_fmac_f32_e32 v129, s13, v37
	v_fmac_f32_e32 v128, s14, v38
	v_fmac_f32_e32 v129, s14, v39
	v_fmac_f32_e32 v128, s15, v40
	v_fmac_f32_e32 v129, s15, v41
	s_add_u32 s48, s48, 0x80
	s_addc_u32 s49, s49, 0
	s_load_dwordx16 s[0:15], s[48:49], 0x0
	v_fma_f32 v130, s64, v42, v76
	v_fma_f32 v131, s64, v43, v77
	v_fmac_f32_e32 v130, s65, v44
	v_fmac_f32_e32 v131, s65, v45
	v_fmac_f32_e32 v130, s66, v46
	v_fmac_f32_e32 v131, s66, v47
	v_fmac_f32_e32 v130, s67, v48
	v_fmac_f32_e32 v131, s67, v49
	v_fmac_f32_e32 v130, s68, v50
	v_fmac_f32_e32 v131, s68, v51
	v_fmac_f32_e32 v130, s69, v52
	v_fmac_f32_e32 v131, s69, v53
	v_fmac_f32_e32 v130, s70, v54
	v_fmac_f32_e32 v131, s70, v55
	v_fmac_f32_e32 v130, s71, v56
	v_fmac_f32_e32 v131, s71, v57
	v_fmac_f32_e32 v130, s72, v58
	v_fmac_f32_e32 v131, s72, v59
	v_fmac_f32_e32 v130, s73, v60
	v_fmac_f32_e32 v131, s73, v61
	v_fmac_f32_e32 v130, s74, v62
	v_fmac_f32_e32 v131, s74, v63
	v_fmac_f32_e32 v130, s75, v64
	v_fmac_f32_e32 v131, s75, v65
	v_fmac_f32_e32 v130, s76, v66
	v_fmac_f32_e32 v131, s76, v67
	v_fmac_f32_e32 v130, s77, v68
	v_fmac_f32_e32 v131, s77, v69
	v_fmac_f32_e32 v130, s78, v70
	v_fmac_f32_e32 v131, s78, v71
	v_fmac_f32_e32 v130, s79, v72
	v_fmac_f32_e32 v131, s79, v73
	s_load_dwordx16 s[64:79], s[48:49], 0x40
	v_mul_f32_e64 v132, |v128|, s33
	v_mul_f32_e64 v133, |v129|, s33
	v_mul_f32_e64 v134, |v130|, s33
	v_mul_f32_e64 v135, |v131|, s33
	v_exp_f32_e32 v132, v132
	v_exp_f32_e32 v133, v133
	v_exp_f32_e32 v134, v134
	v_exp_f32_e32 v135, v135
	v_add_f32_e32 v132, 1.0, v132
	v_add_f32_e32 v133, 1.0, v133
	v_add_f32_e32 v134, 1.0, v134
	v_add_f32_e32 v135, 1.0, v135
	v_log_f32_e32 v136, v132
	v_log_f32_e32 v137, v133
	v_log_f32_e32 v138, v134
	v_log_f32_e32 v139, v135
	v_mul_f32_e32 v140, 0x3f317217, v136
	v_mul_f32_e32 v141, 0x3f317217, v137
	v_mul_f32_e32 v142, 0x3f317217, v138
	v_mul_f32_e32 v143, 0x3f317217, v139
	v_fma_f32 v144, v136, s35, -v140
	v_fma_f32 v145, v137, s35, -v141
	v_fma_f32 v146, v138, s35, -v142
	v_fma_f32 v147, v139, s35, -v143
	v_fmac_f32_e32 v144, 0x3377d1cf, v136
	v_fmac_f32_e32 v145, 0x3377d1cf, v137
	v_fmac_f32_e32 v146, 0x3377d1cf, v138
	v_fmac_f32_e32 v147, 0x3377d1cf, v139
	v_fmac_f32_e32 v144, 0x3f317217, v136
	v_fmac_f32_e32 v145, 0x3f317217, v137
	v_fmac_f32_e32 v146, 0x3f317217, v138
	v_fmac_f32_e32 v147, 0x3f317217, v139
	v_min_f32_e32 v128, 0, v128
	v_min_f32_e32 v129, 0, v129
	v_min_f32_e32 v130, 0, v130
	v_min_f32_e32 v131, 0, v131
	v_sub_f32_e32 v128, v128, v144
	v_sub_f32_e32 v129, v129, v145
	v_sub_f32_e32 v130, v130, v146
	v_sub_f32_e32 v131, v131, v147
	v_mul_f32_e32 v104, 0x3d800000, v128
	v_mul_f32_e32 v105, 0x3d800000, v129
	v_mul_f32_e32 v120, 0x3d800000, v130
	v_mul_f32_e32 v121, 0x3d800000, v131
	s_waitcnt lgkmcnt(0)
	v_fma_f32 v128, s0, v10, v74
	v_fma_f32 v129, s0, v11, v75
	v_fmac_f32_e32 v128, s1, v12
	v_fmac_f32_e32 v129, s1, v13
	v_fmac_f32_e32 v128, s2, v14
	v_fmac_f32_e32 v129, s2, v15
	v_fmac_f32_e32 v128, s3, v16
	v_fmac_f32_e32 v129, s3, v17
	v_fmac_f32_e32 v128, s4, v18
	v_fmac_f32_e32 v129, s4, v19
	v_fmac_f32_e32 v128, s5, v20
	v_fmac_f32_e32 v129, s5, v21
	v_fmac_f32_e32 v128, s6, v22
	v_fmac_f32_e32 v129, s6, v23
	v_fmac_f32_e32 v128, s7, v24
	v_fmac_f32_e32 v129, s7, v25
	v_fmac_f32_e32 v128, s8, v26
	v_fmac_f32_e32 v129, s8, v27
	v_fmac_f32_e32 v128, s9, v28
	v_fmac_f32_e32 v129, s9, v29
	v_fmac_f32_e32 v128, s10, v30
	v_fmac_f32_e32 v129, s10, v31
	v_fmac_f32_e32 v128, s11, v32
	v_fmac_f32_e32 v129, s11, v33
	v_fmac_f32_e32 v128, s12, v34
	v_fmac_f32_e32 v129, s12, v35
	v_fmac_f32_e32 v128, s13, v36
	v_fmac_f32_e32 v129, s13, v37
	v_fmac_f32_e32 v128, s14, v38
	v_fmac_f32_e32 v129, s14, v39
	v_fmac_f32_e32 v128, s15, v40
	v_fmac_f32_e32 v129, s15, v41
	s_add_u32 s48, s48, 0x80
	s_addc_u32 s49, s49, 0
	s_load_dwordx16 s[0:15], s[48:49], 0x0
	v_fma_f32 v130, s64, v42, v76
	v_fma_f32 v131, s64, v43, v77
	v_fmac_f32_e32 v130, s65, v44
	v_fmac_f32_e32 v131, s65, v45
	v_fmac_f32_e32 v130, s66, v46
	v_fmac_f32_e32 v131, s66, v47
	v_fmac_f32_e32 v130, s67, v48
	v_fmac_f32_e32 v131, s67, v49
	v_fmac_f32_e32 v130, s68, v50
	v_fmac_f32_e32 v131, s68, v51
	v_fmac_f32_e32 v130, s69, v52
	v_fmac_f32_e32 v131, s69, v53
	v_fmac_f32_e32 v130, s70, v54
	v_fmac_f32_e32 v131, s70, v55
	v_fmac_f32_e32 v130, s71, v56
	v_fmac_f32_e32 v131, s71, v57
	v_fmac_f32_e32 v130, s72, v58
	v_fmac_f32_e32 v131, s72, v59
	v_fmac_f32_e32 v130, s73, v60
	v_fmac_f32_e32 v131, s73, v61
	v_fmac_f32_e32 v130, s74, v62
	v_fmac_f32_e32 v131, s74, v63
	v_fmac_f32_e32 v130, s75, v64
	v_fmac_f32_e32 v131, s75, v65
	v_fmac_f32_e32 v130, s76, v66
	v_fmac_f32_e32 v131, s76, v67
	v_fmac_f32_e32 v130, s77, v68
	v_fmac_f32_e32 v131, s77, v69
	v_fmac_f32_e32 v130, s78, v70
	v_fmac_f32_e32 v131, s78, v71
	v_fmac_f32_e32 v130, s79, v72
	v_fmac_f32_e32 v131, s79, v73
	s_load_dwordx16 s[64:79], s[48:49], 0x40
	v_mul_f32_e64 v132, |v128|, s33
	v_mul_f32_e64 v133, |v129|, s33
	v_mul_f32_e64 v134, |v130|, s33
	v_mul_f32_e64 v135, |v131|, s33
	v_exp_f32_e32 v132, v132
	v_exp_f32_e32 v133, v133
	v_exp_f32_e32 v134, v134
	v_exp_f32_e32 v135, v135
	v_add_f32_e32 v132, 1.0, v132
	v_add_f32_e32 v133, 1.0, v133
	v_add_f32_e32 v134, 1.0, v134
	v_add_f32_e32 v135, 1.0, v135
	v_log_f32_e32 v136, v132
	v_log_f32_e32 v137, v133
	v_log_f32_e32 v138, v134
	v_log_f32_e32 v139, v135
	v_mul_f32_e32 v140, 0x3f317217, v136
	v_mul_f32_e32 v141, 0x3f317217, v137
	v_mul_f32_e32 v142, 0x3f317217, v138
	v_mul_f32_e32 v143, 0x3f317217, v139
	v_fma_f32 v144, v136, s35, -v140
	v_fma_f32 v145, v137, s35, -v141
	v_fma_f32 v146, v138, s35, -v142
	v_fma_f32 v147, v139, s35, -v143
	v_fmac_f32_e32 v144, 0x3377d1cf, v136
	v_fmac_f32_e32 v145, 0x3377d1cf, v137
	v_fmac_f32_e32 v146, 0x3377d1cf, v138
	v_fmac_f32_e32 v147, 0x3377d1cf, v139
	v_fmac_f32_e32 v144, 0x3f317217, v136
	v_fmac_f32_e32 v145, 0x3f317217, v137
	v_fmac_f32_e32 v146, 0x3f317217, v138
	v_fmac_f32_e32 v147, 0x3f317217, v139
	v_min_f32_e32 v128, 0, v128
	v_min_f32_e32 v129, 0, v129
	v_min_f32_e32 v130, 0, v130
	v_min_f32_e32 v131, 0, v131
	v_sub_f32_e32 v128, v128, v144
	v_sub_f32_e32 v129, v129, v145
	v_sub_f32_e32 v130, v130, v146
	v_sub_f32_e32 v131, v131, v147
	v_mul_f32_e32 v106, 0x3d800000, v128
	v_mul_f32_e32 v107, 0x3d800000, v129
	v_mul_f32_e32 v122, 0x3d800000, v130
	v_mul_f32_e32 v123, 0x3d800000, v131
	s_waitcnt lgkmcnt(0)
	v_fma_f32 v128, s0, v10, v74
	v_fma_f32 v129, s0, v11, v75
	v_fmac_f32_e32 v128, s1, v12
	v_fmac_f32_e32 v129, s1, v13
	v_fmac_f32_e32 v128, s2, v14
	v_fmac_f32_e32 v129, s2, v15
	v_fmac_f32_e32 v128, s3, v16
	v_fmac_f32_e32 v129, s3, v17
	v_fmac_f32_e32 v128, s4, v18
	v_fmac_f32_e32 v129, s4, v19
	v_fmac_f32_e32 v128, s5, v20
	v_fmac_f32_e32 v129, s5, v21
	v_fmac_f32_e32 v128, s6, v22
	v_fmac_f32_e32 v129, s6, v23
	v_fmac_f32_e32 v128, s7, v24
	v_fmac_f32_e32 v129, s7, v25
	v_fmac_f32_e32 v128, s8, v26
	v_fmac_f32_e32 v129, s8, v27
	v_fmac_f32_e32 v128, s9, v28
	v_fmac_f32_e32 v129, s9, v29
	v_fmac_f32_e32 v128, s10, v30
	v_fmac_f32_e32 v129, s10, v31
	v_fmac_f32_e32 v128, s11, v32
	v_fmac_f32_e32 v129, s11, v33
	v_fmac_f32_e32 v128, s12, v34
	v_fmac_f32_e32 v129, s12, v35
	v_fmac_f32_e32 v128, s13, v36
	v_fmac_f32_e32 v129, s13, v37
	v_fmac_f32_e32 v128, s14, v38
	v_fmac_f32_e32 v129, s14, v39
	v_fmac_f32_e32 v128, s15, v40
	v_fmac_f32_e32 v129, s15, v41
	s_add_u32 s48, s48, 0x80
	s_addc_u32 s49, s49, 0
	s_load_dwordx16 s[0:15], s[48:49], 0x0
	v_fma_f32 v130, s64, v42, v76
	v_fma_f32 v131, s64, v43, v77
	v_fmac_f32_e32 v130, s65, v44
	v_fmac_f32_e32 v131, s65, v45
	v_fmac_f32_e32 v130, s66, v46
	v_fmac_f32_e32 v131, s66, v47
	v_fmac_f32_e32 v130, s67, v48
	v_fmac_f32_e32 v131, s67, v49
	v_fmac_f32_e32 v130, s68, v50
	v_fmac_f32_e32 v131, s68, v51
	v_fmac_f32_e32 v130, s69, v52
	v_fmac_f32_e32 v131, s69, v53
	v_fmac_f32_e32 v130, s70, v54
	v_fmac_f32_e32 v131, s70, v55
	v_fmac_f32_e32 v130, s71, v56
	v_fmac_f32_e32 v131, s71, v57
	v_fmac_f32_e32 v130, s72, v58
	v_fmac_f32_e32 v131, s72, v59
	v_fmac_f32_e32 v130, s73, v60
	v_fmac_f32_e32 v131, s73, v61
	v_fmac_f32_e32 v130, s74, v62
	v_fmac_f32_e32 v131, s74, v63
	v_fmac_f32_e32 v130, s75, v64
	v_fmac_f32_e32 v131, s75, v65
	v_fmac_f32_e32 v130, s76, v66
	v_fmac_f32_e32 v131, s76, v67
	v_fmac_f32_e32 v130, s77, v68
	v_fmac_f32_e32 v131, s77, v69
	v_fmac_f32_e32 v130, s78, v70
	v_fmac_f32_e32 v131, s78, v71
	v_fmac_f32_e32 v130, s79, v72
	v_fmac_f32_e32 v131, s79, v73
	s_load_dwordx16 s[64:79], s[48:49], 0x40
	v_mul_f32_e64 v132, |v128|, s33
	v_mul_f32_e64 v133, |v129|, s33
	v_mul_f32_e64 v134, |v130|, s33
	v_mul_f32_e64 v135, |v131|, s33
	v_exp_f32_e32 v132, v132
	v_exp_f32_e32 v133, v133
	v_exp_f32_e32 v134, v134
	v_exp_f32_e32 v135, v135
	v_add_f32_e32 v132, 1.0, v132
	v_add_f32_e32 v133, 1.0, v133
	v_add_f32_e32 v134, 1.0, v134
	v_add_f32_e32 v135, 1.0, v135
	v_log_f32_e32 v136, v132
	v_log_f32_e32 v137, v133
	v_log_f32_e32 v138, v134
	v_log_f32_e32 v139, v135
	v_mul_f32_e32 v140, 0x3f317217, v136
	v_mul_f32_e32 v141, 0x3f317217, v137
	v_mul_f32_e32 v142, 0x3f317217, v138
	v_mul_f32_e32 v143, 0x3f317217, v139
	v_fma_f32 v144, v136, s35, -v140
	v_fma_f32 v145, v137, s35, -v141
	v_fma_f32 v146, v138, s35, -v142
	v_fma_f32 v147, v139, s35, -v143
	v_fmac_f32_e32 v144, 0x3377d1cf, v136
	v_fmac_f32_e32 v145, 0x3377d1cf, v137
	v_fmac_f32_e32 v146, 0x3377d1cf, v138
	v_fmac_f32_e32 v147, 0x3377d1cf, v139
	v_fmac_f32_e32 v144, 0x3f317217, v136
	v_fmac_f32_e32 v145, 0x3f317217, v137
	v_fmac_f32_e32 v146, 0x3f317217, v138
	v_fmac_f32_e32 v147, 0x3f317217, v139
	v_min_f32_e32 v128, 0, v128
	v_min_f32_e32 v129, 0, v129
	v_min_f32_e32 v130, 0, v130
	v_min_f32_e32 v131, 0, v131
	v_sub_f32_e32 v128, v128, v144
	v_sub_f32_e32 v129, v129, v145
	v_sub_f32_e32 v130, v130, v146
	v_sub_f32_e32 v131, v131, v147
	v_mul_f32_e32 v108, 0x3d800000, v128
	v_mul_f32_e32 v109, 0x3d800000, v129
	v_mul_f32_e32 v124, 0x3d800000, v130
	v_mul_f32_e32 v125, 0x3d800000, v131
	s_waitcnt lgkmcnt(0)
	v_fma_f32 v128, s0, v10, v74
	v_fma_f32 v129, s0, v11, v75
	v_fmac_f32_e32 v128, s1, v12
	v_fmac_f32_e32 v129, s1, v13
	v_fmac_f32_e32 v128, s2, v14
	v_fmac_f32_e32 v129, s2, v15
	v_fmac_f32_e32 v128, s3, v16
	v_fmac_f32_e32 v129, s3, v17
	v_fmac_f32_e32 v128, s4, v18
	v_fmac_f32_e32 v129, s4, v19
	v_fmac_f32_e32 v128, s5, v20
	v_fmac_f32_e32 v129, s5, v21
	v_fmac_f32_e32 v128, s6, v22
	v_fmac_f32_e32 v129, s6, v23
	v_fmac_f32_e32 v128, s7, v24
	v_fmac_f32_e32 v129, s7, v25
	v_fmac_f32_e32 v128, s8, v26
	v_fmac_f32_e32 v129, s8, v27
	v_fmac_f32_e32 v128, s9, v28
	v_fmac_f32_e32 v129, s9, v29
	v_fmac_f32_e32 v128, s10, v30
	v_fmac_f32_e32 v129, s10, v31
	v_fmac_f32_e32 v128, s11, v32
	v_fmac_f32_e32 v129, s11, v33
	v_fmac_f32_e32 v128, s12, v34
	v_fmac_f32_e32 v129, s12, v35
	v_fmac_f32_e32 v128, s13, v36
	v_fmac_f32_e32 v129, s13, v37
	v_fmac_f32_e32 v128, s14, v38
	v_fmac_f32_e32 v129, s14, v39
	v_fmac_f32_e32 v128, s15, v40
	v_fmac_f32_e32 v129, s15, v41
	v_fma_f32 v130, s64, v42, v76
	v_fma_f32 v131, s64, v43, v77
	v_fmac_f32_e32 v130, s65, v44
	v_fmac_f32_e32 v131, s65, v45
	v_fmac_f32_e32 v130, s66, v46
	v_fmac_f32_e32 v131, s66, v47
	v_fmac_f32_e32 v130, s67, v48
	v_fmac_f32_e32 v131, s67, v49
	v_fmac_f32_e32 v130, s68, v50
	v_fmac_f32_e32 v131, s68, v51
	v_fmac_f32_e32 v130, s69, v52
	v_fmac_f32_e32 v131, s69, v53
	v_fmac_f32_e32 v130, s70, v54
	v_fmac_f32_e32 v131, s70, v55
	v_fmac_f32_e32 v130, s71, v56
	v_fmac_f32_e32 v131, s71, v57
	v_fmac_f32_e32 v130, s72, v58
	v_fmac_f32_e32 v131, s72, v59
	v_fmac_f32_e32 v130, s73, v60
	v_fmac_f32_e32 v131, s73, v61
	v_fmac_f32_e32 v130, s74, v62
	v_fmac_f32_e32 v131, s74, v63
	v_fmac_f32_e32 v130, s75, v64
	v_fmac_f32_e32 v131, s75, v65
	v_fmac_f32_e32 v130, s76, v66
	v_fmac_f32_e32 v131, s76, v67
	v_fmac_f32_e32 v130, s77, v68
	v_fmac_f32_e32 v131, s77, v69
	v_fmac_f32_e32 v130, s78, v70
	v_fmac_f32_e32 v131, s78, v71
	v_fmac_f32_e32 v130, s79, v72
	v_fmac_f32_e32 v131, s79, v73
	v_mul_f32_e64 v132, |v128|, s33
	v_mul_f32_e64 v133, |v129|, s33
	v_mul_f32_e64 v134, |v130|, s33
	v_mul_f32_e64 v135, |v131|, s33
	v_exp_f32_e32 v132, v132
	v_exp_f32_e32 v133, v133
	v_exp_f32_e32 v134, v134
	v_exp_f32_e32 v135, v135
	v_add_f32_e32 v132, 1.0, v132
	v_add_f32_e32 v133, 1.0, v133
	v_add_f32_e32 v134, 1.0, v134
	v_add_f32_e32 v135, 1.0, v135
	v_log_f32_e32 v136, v132
	v_log_f32_e32 v137, v133
	v_log_f32_e32 v138, v134
	v_log_f32_e32 v139, v135
	v_mul_f32_e32 v140, 0x3f317217, v136
	v_mul_f32_e32 v141, 0x3f317217, v137
	v_mul_f32_e32 v142, 0x3f317217, v138
	v_mul_f32_e32 v143, 0x3f317217, v139
	v_fma_f32 v144, v136, s35, -v140
	v_fma_f32 v145, v137, s35, -v141
	v_fma_f32 v146, v138, s35, -v142
	v_fma_f32 v147, v139, s35, -v143
	v_fmac_f32_e32 v144, 0x3377d1cf, v136
	v_fmac_f32_e32 v145, 0x3377d1cf, v137
	v_fmac_f32_e32 v146, 0x3377d1cf, v138
	v_fmac_f32_e32 v147, 0x3377d1cf, v139
	v_fmac_f32_e32 v144, 0x3f317217, v136
	v_fmac_f32_e32 v145, 0x3f317217, v137
	v_fmac_f32_e32 v146, 0x3f317217, v138
	v_fmac_f32_e32 v147, 0x3f317217, v139
	v_min_f32_e32 v128, 0, v128
	v_min_f32_e32 v129, 0, v129
	v_min_f32_e32 v130, 0, v130
	v_min_f32_e32 v131, 0, v131
	v_sub_f32_e32 v128, v128, v144
	v_sub_f32_e32 v129, v129, v145
	v_sub_f32_e32 v130, v130, v146
	v_sub_f32_e32 v131, v131, v147
	v_mul_f32_e32 v110, 0x3d800000, v128
	v_mul_f32_e32 v111, 0x3d800000, v129
	v_mul_f32_e32 v126, 0x3d800000, v130
	v_mul_f32_e32 v127, 0x3d800000, v131
	v_readlane_b32 s69, v251, 49
	s_nop 3
	s_add_i32 s51, s34, s69
	s_cmpk_lt_i32 s51, 0x480
	s_cbranch_scc0 .Lp7_no_prefetch
	s_mul_hi_u32 s80, s51, 0x1c71c72
	s_mul_i32 s92, s80, 144
	s_sub_i32 s92, s51, s92
	s_mul_hi_u32 s82, s92, 0x71c71c8
	s_mul_i32 s93, s82, 36
	s_sub_i32 s81, s92, s93
	s_lshl_b32 s92, s80, 8
	s_lshl_b32 s93, s81, 6
	s_add_i32 s92, s92, s93
	s_addk_i32 s92, 0x4000
	s_lshl_b32 s94, s80, 11
	s_add_i32 s94, s94, s93
	s_addk_i32 s94, 0xff00
	s_cmp_lt_u32 s81, 4
	s_cselect_b32 s83, s92, s94
	s_lshl_b32 s92, s32, 3
	s_add_i32 s83, s83, s92
	s_lshl_b32 s95, s82, 8
	s_mul_i32 s92, s83, 0x1800
	s_add_u32 s92, s92, s95
	s_add_u32 s84, s96, s92
	s_addc_u32 s85, s97, 0
	s_lshl_b32 s92, s83, 10
	s_add_u32 s92, s92, s95
	s_add_u32 s86, s88, 0xa27d000
	s_addc_u32 s87, s89, 0
	s_add_u32 s86, s86, s92
	s_addc_u32 s87, s87, 0
	s_add_u32 s98, s86, 0x1000000
	s_addc_u32 s99, s87, 0
	s_lshl_b32 s92, s83, 7
	s_add_u32 s100, s88, 0xf1d000
	s_addc_u32 s101, s89, 0
	s_add_u32 s100, s100, s92
	s_addc_u32 s101, s101, 0
	s_lshl_b32 s95, s82, 9
	v_readlane_b32 s52, v251, 18
	v_readlane_b32 s53, v251, 19
	s_nop 3
	s_add_u32 s52, s52, s95
	s_addc_u32 s53, s53, 0
	global_load_dwordx2 v[10:11], v3, s[52:53]
	global_load_dwordx2 v[12:13], v3, s[52:53] offset:2048
	s_add_u32 s52, s52, 0x1000
	s_addc_u32 s53, s53, 0
	global_load_dwordx2 v[14:15], v3, s[52:53]
	global_load_dwordx2 v[16:17], v3, s[52:53] offset:2048
	s_add_u32 s52, s52, 0x1000
	s_addc_u32 s53, s53, 0
	global_load_dwordx2 v[18:19], v3, s[52:53]
	global_load_dwordx2 v[20:21], v3, s[52:53] offset:2048
	s_add_u32 s52, s52, 0x1000
	s_addc_u32 s53, s53, 0
	global_load_dwordx2 v[22:23], v3, s[52:53]
	global_load_dwordx2 v[24:25], v3, s[52:53] offset:2048
	s_add_u32 s52, s52, 0x1000
	s_addc_u32 s53, s53, 0
	global_load_dwordx2 v[26:27], v3, s[52:53]
	global_load_dwordx2 v[28:29], v3, s[52:53] offset:2048
	s_add_u32 s52, s52, 0x1000
	s_addc_u32 s53, s53, 0
	global_load_dwordx2 v[30:31], v3, s[52:53]
	global_load_dwordx2 v[32:33], v3, s[52:53] offset:2048
	s_add_u32 s52, s52, 0x1000
	s_addc_u32 s53, s53, 0
	global_load_dwordx2 v[34:35], v3, s[52:53]
	global_load_dwordx2 v[36:37], v3, s[52:53] offset:2048
	s_add_u32 s52, s52, 0x1000
	s_addc_u32 s53, s53, 0
	global_load_dwordx2 v[38:39], v3, s[52:53]
	global_load_dwordx2 v[40:41], v3, s[52:53] offset:2048
	v_readlane_b32 s52, v251, 24
	v_readlane_b32 s53, v251, 25
	s_nop 3
	s_add_u32 s52, s52, s95
	s_addc_u32 s53, s53, 0
	global_load_dwordx2 v[42:43], v3, s[52:53]
	global_load_dwordx2 v[44:45], v3, s[52:53] offset:2048
	s_add_u32 s52, s52, 0x1000
	s_addc_u32 s53, s53, 0
	global_load_dwordx2 v[46:47], v3, s[52:53]
	global_load_dwordx2 v[48:49], v3, s[52:53] offset:2048
	s_add_u32 s52, s52, 0x1000
	s_addc_u32 s53, s53, 0
	global_load_dwordx2 v[50:51], v3, s[52:53]
	global_load_dwordx2 v[52:53], v3, s[52:53] offset:2048
	s_add_u32 s52, s52, 0x1000
	s_addc_u32 s53, s53, 0
	global_load_dwordx2 v[54:55], v3, s[52:53]
	global_load_dwordx2 v[56:57], v3, s[52:53] offset:2048
	s_add_u32 s52, s52, 0x1000
	s_addc_u32 s53, s53, 0
	global_load_dwordx2 v[58:59], v3, s[52:53]
	global_load_dwordx2 v[60:61], v3, s[52:53] offset:2048
	s_add_u32 s52, s52, 0x1000
	s_addc_u32 s53, s53, 0
	global_load_dwordx2 v[62:63], v3, s[52:53]
	global_load_dwordx2 v[64:65], v3, s[52:53] offset:2048
	s_add_u32 s52, s52, 0x1000
	s_addc_u32 s53, s53, 0
	global_load_dwordx2 v[66:67], v3, s[52:53]
	global_load_dwordx2 v[68:69], v3, s[52:53] offset:2048
	s_add_u32 s52, s52, 0x1000
	s_addc_u32 s53, s53, 0
	global_load_dwordx2 v[70:71], v3, s[52:53]
	global_load_dwordx2 v[72:73], v3, s[52:53] offset:2048
	v_readlane_b32 s52, v251, 20
	v_readlane_b32 s53, v251, 21
	s_nop 3
	s_add_u32 s52, s52, s95
	s_addc_u32 s53, s53, 0
	global_load_dwordx2 v[74:75], v3, s[52:53]
	v_readlane_b32 s52, v251, 26
	v_readlane_b32 s53, v251, 27
	s_nop 3
	s_add_u32 s52, s52, s95
	s_addc_u32 s53, s53, 0
	global_load_dwordx2 v[76:77], v3, s[52:53]
	s_load_dwordx16 s[0:15], s[100:101], 0x0
	s_load_dwordx16 s[64:79], s[100:101], 0x40
	s_mov_b64 s[52:53], s[84:85]
	global_load_dword v200, v2, s[52:53] offset:1024
	s_add_u32 s52, s52, 0x1800
	s_addc_u32 s53, s53, 0
	global_load_dword v201, v2, s[52:53] offset:1024
	s_add_u32 s52, s52, 0x1800
	s_addc_u32 s53, s53, 0
	global_load_dword v202, v2, s[52:53] offset:1024
	s_add_u32 s52, s52, 0x1800
	s_addc_u32 s53, s53, 0
	global_load_dword v203, v2, s[52:53] offset:1024
	s_add_u32 s52, s52, 0x1800
	s_addc_u32 s53, s53, 0
	global_load_dword v204, v2, s[52:53] offset:1024
	s_add_u32 s52, s52, 0x1800
	s_addc_u32 s53, s53, 0
	global_load_dword v205, v2, s[52:53] offset:1024
	s_add_u32 s52, s52, 0x1800
	s_addc_u32 s53, s53, 0
	global_load_dword v206, v2, s[52:53] offset:1024
	s_add_u32 s52, s52, 0x1800
	s_addc_u32 s53, s53, 0
	global_load_dword v207, v2, s[52:53] offset:1024
	s_cmp_lt_u32 s81, 4
	s_cbranch_scc1 .Lp7_noq_load_next
	s_mov_b64 s[52:53], s[84:85]
	global_load_dword v208, v2, s[52:53]
	s_add_u32 s52, s52, 0x1800
	s_addc_u32 s53, s53, 0
	global_load_dword v209, v2, s[52:53]
	s_add_u32 s52, s52, 0x1800
	s_addc_u32 s53, s53, 0
	global_load_dword v210, v2, s[52:53]
	s_add_u32 s52, s52, 0x1800
	s_addc_u32 s53, s53, 0
	global_load_dword v211, v2, s[52:53]
	s_add_u32 s52, s52, 0x1800
	s_addc_u32 s53, s53, 0
	global_load_dword v212, v2, s[52:53]
	s_add_u32 s52, s52, 0x1800
	s_addc_u32 s53, s53, 0
	global_load_dword v213, v2, s[52:53]
	s_add_u32 s52, s52, 0x1800
	s_addc_u32 s53, s53, 0
	global_load_dword v214, v2, s[52:53]
	s_add_u32 s52, s52, 0x1800
	s_addc_u32 s53, s53, 0
	global_load_dword v215, v2, s[52:53]
.Lp7_noq_load_next:
.Lp7_no_prefetch:
	v_add_f32_e32 v98, v98, v96
	v_add_f32_e32 v99, v99, v97
	v_add_f32_e32 v100, v100, v98
	v_add_f32_e32 v101, v101, v99
	v_add_f32_e32 v102, v102, v100
	v_add_f32_e32 v103, v103, v101
	v_add_f32_e32 v104, v104, v102
	v_add_f32_e32 v105, v105, v103
	v_add_f32_e32 v106, v106, v104
	v_add_f32_e32 v107, v107, v105
	v_add_f32_e32 v108, v108, v106
	v_add_f32_e32 v109, v109, v107
	v_add_f32_e32 v110, v110, v108
	v_add_f32_e32 v111, v111, v109
	v_add_f32_e32 v124, v124, v126
	v_add_f32_e32 v125, v125, v127
	v_add_f32_e32 v122, v122, v124
	v_add_f32_e32 v123, v123, v125
	v_add_f32_e32 v120, v120, v122
	v_add_f32_e32 v121, v121, v123
	v_add_f32_e32 v118, v118, v120
	v_add_f32_e32 v119, v119, v121
	v_add_f32_e32 v116, v116, v118
	v_add_f32_e32 v117, v117, v119
	v_add_f32_e32 v114, v114, v116
	v_add_f32_e32 v115, v115, v117
	v_add_f32_e32 v112, v112, v114
	v_add_f32_e32 v113, v113, v115
	s_lshl_b32 s92, s50, 13
	s_lshl_b32 s93, s32, 9
	s_add_i32 s93, s93, s92
	v_add_u32_e32 v184, s93, v3
	v_add_u32_e32 v185, s92, v3
	ds_write_b64 v184, v[110:111]
	ds_write_b64 v184, v[112:113] offset:4096
	s_waitcnt lgkmcnt(0)
	s_barrier
	ds_read_b64 v[152:153], v185 offset:0
	ds_read_b64 v[154:155], v185 offset:512
	ds_read_b64 v[156:157], v185 offset:1024
	ds_read_b64 v[158:159], v185 offset:1536
	ds_read_b64 v[160:161], v185 offset:2048
	ds_read_b64 v[162:163], v185 offset:2560
	ds_read_b64 v[164:165], v185 offset:3072
	ds_read_b64 v[166:167], v185 offset:3584
	ds_read_b64 v[168:169], v185 offset:4096
	ds_read_b64 v[170:171], v185 offset:4608
	ds_read_b64 v[172:173], v185 offset:5120
	ds_read_b64 v[174:175], v185 offset:5632
	ds_read_b64 v[176:177], v185 offset:6144
	ds_read_b64 v[178:179], v185 offset:6656
	ds_read_b64 v[180:181], v185 offset:7168
	ds_read_b64 v[182:183], v185 offset:7680
	v_mov_b32_e32 v132, 0
	v_mov_b32_e32 v133, 0
	v_mov_b32_e32 v134, 0
	v_mov_b32_e32 v135, 0
	s_waitcnt lgkmcnt(0)
	s_cmp_le_u32 s32, 0
	s_cbranch_scc1 .Lp7_offf_done
	v_add_f32_e32 v132, v132, v152
	v_add_f32_e32 v133, v133, v153
	s_cmp_le_u32 s32, 1
	s_cbranch_scc1 .Lp7_offf_done
	v_add_f32_e32 v132, v132, v154
	v_add_f32_e32 v133, v133, v155
	s_cmp_le_u32 s32, 2
	s_cbranch_scc1 .Lp7_offf_done
	v_add_f32_e32 v132, v132, v156
	v_add_f32_e32 v133, v133, v157
	s_cmp_le_u32 s32, 3
	s_cbranch_scc1 .Lp7_offf_done
	v_add_f32_e32 v132, v132, v158
	v_add_f32_e32 v133, v133, v159
	s_cmp_le_u32 s32, 4
	s_cbranch_scc1 .Lp7_offf_done
	v_add_f32_e32 v132, v132, v160
	v_add_f32_e32 v133, v133, v161
	s_cmp_le_u32 s32, 5
	s_cbranch_scc1 .Lp7_offf_done
	v_add_f32_e32 v132, v132, v162
	v_add_f32_e32 v133, v133, v163
	s_cmp_le_u32 s32, 6
	s_cbranch_scc1 .Lp7_offf_done
	v_add_f32_e32 v132, v132, v164
	v_add_f32_e32 v133, v133, v165

.Lp7_offb_done:
	s_cmp_lg_u32 s32, 0
	s_cbranch_scc1 .Lp7_dec_done
	v_add_f32_e32 v136, v152, v154
	v_add_f32_e32 v137, v153, v155
	v_add_f32_e32 v138, v168, v170
	v_add_f32_e32 v139, v169, v171
	v_add_f32_e32 v136, v136, v156
	v_add_f32_e32 v137, v137, v157
	v_add_f32_e32 v138, v138, v172
	v_add_f32_e32 v139, v139, v173
	v_add_f32_e32 v136, v136, v158
	v_add_f32_e32 v137, v137, v159
	v_add_f32_e32 v138, v138, v174
	v_add_f32_e32 v139, v139, v175
	v_add_f32_e32 v136, v136, v160
	v_add_f32_e32 v137, v137, v161
	v_add_f32_e32 v138, v138, v176
	v_add_f32_e32 v139, v139, v177
	v_add_f32_e32 v136, v136, v162
	v_add_f32_e32 v137, v137, v163
	v_add_f32_e32 v138, v138, v178
	v_add_f32_e32 v139, v139, v179
	v_add_f32_e32 v136, v136, v164
	v_add_f32_e32 v137, v137, v165
	v_add_f32_e32 v138, v138, v180
	v_add_f32_e32 v139, v139, v181
	v_add_f32_e32 v136, v136, v166
	v_add_f32_e32 v137, v137, v167
	v_add_f32_e32 v138, v138, v182
	v_add_f32_e32 v139, v139, v183
	v_mul_f32_e32 v136, 0x3fb8aa3b, v136
	v_mul_f32_e32 v137, 0x3fb8aa3b, v137
	v_mul_f32_e32 v138, 0x3fb8aa3b, v138
	v_mul_f32_e32 v139, 0x3fb8aa3b, v139
	v_exp_f32_e32 v136, v136
	v_exp_f32_e32 v137, v137
	v_exp_f32_e32 v138, v138
	v_exp_f32_e32 v139, v139
	s_lshl_b32 s92, s38, 2
	s_add_i32 s92, s92, s40
	s_mul_i32 s92, s92, 36
	s_add_i32 s92, s92, s39
	s_lshl_b32 s92, s92, 9
	s_add_u32 s52, s88, 0x115d000
	s_addc_u32 s53, s89, 0
	s_add_u32 s52, s52, s92
	s_addc_u32 s53, s53, 0
	global_store_dwordx2 v3, v[136:137], s[52:53]
	s_add_u32 s52, s52, 0x90000
	s_addc_u32 s53, s53, 0
	global_store_dwordx2 v3, v[138:139], s[52:53]
.Lp7_dec_done:
	s_mov_b64 s[52:53], s[42:43]
	s_mov_b64 s[54:55], s[46:47]
	v_add_f32_e32 v136, v96, v132
	v_add_f32_e32 v137, v97, v133
	v_add_f32_e32 v138, v112, v134
	v_add_f32_e32 v139, v113, v135
	v_mul_f32_e32 v136, 0xbfb8aa3b, v136
	v_mul_f32_e32 v137, 0xbfb8aa3b, v137
	v_mul_f32_e32 v138, 0xbfb8aa3b, v138
	v_mul_f32_e32 v139, 0xbfb8aa3b, v139
	v_exp_f32_e32 v136, v136
	v_exp_f32_e32 v137, v137
	v_exp_f32_e32 v138, v138
	v_exp_f32_e32 v139, v139
	v_lshlrev_b32_e32 v140, 16, v80
	v_and_b32_e32 v141, 0xffff0000, v80
	v_mul_f32_e32 v136, v140, v136
	v_mul_f32_e32 v137, v141, v137
	v_mul_f32_e32 v138, v140, v138
	v_mul_f32_e32 v139, v141, v139
	v_cvt_pk_bf16_f32 v142, v136, v137
	v_cvt_pk_bf16_f32 v143, v138, v139
	global_store_dword v2, v142, s[52:53] offset:1024
	global_store_dword v2, v143, s[54:55]
	s_add_u32 s52, s52, 0x1800
	s_addc_u32 s53, s53, 0
	s_add_u32 s54, s54, 0x400
	s_addc_u32 s55, s55, 0
	v_add_f32_e32 v136, v98, v132
	v_add_f32_e32 v137, v99, v133
	v_add_f32_e32 v138, v114, v134
	v_add_f32_e32 v139, v115, v135
	v_mul_f32_e32 v136, 0xbfb8aa3b, v136
	v_mul_f32_e32 v137, 0xbfb8aa3b, v137
	v_mul_f32_e32 v138, 0xbfb8aa3b, v138
	v_mul_f32_e32 v139, 0xbfb8aa3b, v139
	v_exp_f32_e32 v136, v136
	v_exp_f32_e32 v137, v137
	v_exp_f32_e32 v138, v138
	v_exp_f32_e32 v139, v139
	v_lshlrev_b32_e32 v140, 16, v81
	v_and_b32_e32 v141, 0xffff0000, v81
	v_mul_f32_e32 v136, v140, v136
	v_mul_f32_e32 v137, v141, v137
	v_mul_f32_e32 v138, v140, v138
	v_mul_f32_e32 v139, v141, v139
	v_cvt_pk_bf16_f32 v142, v136, v137
	v_cvt_pk_bf16_f32 v143, v138, v139
	global_store_dword v2, v142, s[52:53] offset:1024
	global_store_dword v2, v143, s[54:55]
	s_add_u32 s52, s52, 0x1800
	s_addc_u32 s53, s53, 0
	s_add_u32 s54, s54, 0x400
	s_addc_u32 s55, s55, 0
	v_add_f32_e32 v136, v100, v132
	v_add_f32_e32 v137, v101, v133
	v_add_f32_e32 v138, v116, v134
	v_add_f32_e32 v139, v117, v135
	v_mul_f32_e32 v136, 0xbfb8aa3b, v136
	v_mul_f32_e32 v137, 0xbfb8aa3b, v137
	v_mul_f32_e32 v138, 0xbfb8aa3b, v138
	v_mul_f32_e32 v139, 0xbfb8aa3b, v139
	v_exp_f32_e32 v136, v136
	v_exp_f32_e32 v137, v137
	v_exp_f32_e32 v138, v138
	v_exp_f32_e32 v139, v139
	v_lshlrev_b32_e32 v140, 16, v82
	v_and_b32_e32 v141, 0xffff0000, v82
	v_mul_f32_e32 v136, v140, v136
	v_mul_f32_e32 v137, v141, v137
	v_mul_f32_e32 v138, v140, v138
	v_mul_f32_e32 v139, v141, v139
	v_cvt_pk_bf16_f32 v142, v136, v137
	v_cvt_pk_bf16_f32 v143, v138, v139
	global_store_dword v2, v142, s[52:53] offset:1024
	global_store_dword v2, v143, s[54:55]
	s_add_u32 s52, s52, 0x1800
	s_addc_u32 s53, s53, 0
	s_add_u32 s54, s54, 0x400
	s_addc_u32 s55, s55, 0
	v_add_f32_e32 v136, v102, v132
	v_add_f32_e32 v137, v103, v133
	v_add_f32_e32 v138, v118, v134
	v_add_f32_e32 v139, v119, v135
	v_mul_f32_e32 v136, 0xbfb8aa3b, v136
	v_mul_f32_e32 v137, 0xbfb8aa3b, v137
	v_mul_f32_e32 v138, 0xbfb8aa3b, v138
	v_mul_f32_e32 v139, 0xbfb8aa3b, v139
	v_exp_f32_e32 v136, v136
	v_exp_f32_e32 v137, v137
	v_exp_f32_e32 v138, v138
	v_exp_f32_e32 v139, v139
	v_lshlrev_b32_e32 v140, 16, v83
	v_and_b32_e32 v141, 0xffff0000, v83
	v_mul_f32_e32 v136, v140, v136
	v_mul_f32_e32 v137, v141, v137
	v_mul_f32_e32 v138, v140, v138
	v_mul_f32_e32 v139, v141, v139
	v_cvt_pk_bf16_f32 v142, v136, v137
	v_cvt_pk_bf16_f32 v143, v138, v139
	global_store_dword v2, v142, s[52:53] offset:1024
	global_store_dword v2, v143, s[54:55]
	s_add_u32 s52, s52, 0x1800
	s_addc_u32 s53, s53, 0
	s_add_u32 s54, s54, 0x400
	s_addc_u32 s55, s55, 0
	v_add_f32_e32 v136, v104, v132
	v_add_f32_e32 v137, v105, v133
	v_add_f32_e32 v138, v120, v134
	v_add_f32_e32 v139, v121, v135
	v_mul_f32_e32 v136, 0xbfb8aa3b, v136
	v_mul_f32_e32 v137, 0xbfb8aa3b, v137
	v_mul_f32_e32 v138, 0xbfb8aa3b, v138
	v_mul_f32_e32 v139, 0xbfb8aa3b, v139
	v_exp_f32_e32 v136, v136
	v_exp_f32_e32 v137, v137
	v_exp_f32_e32 v138, v138
	v_exp_f32_e32 v139, v139
	v_lshlrev_b32_e32 v140, 16, v84
	v_and_b32_e32 v141, 0xffff0000, v84
	v_mul_f32_e32 v136, v140, v136
	v_mul_f32_e32 v137, v141, v137
	v_mul_f32_e32 v138, v140, v138
	v_mul_f32_e32 v139, v141, v139
	v_cvt_pk_bf16_f32 v142, v136, v137
	v_cvt_pk_bf16_f32 v143, v138, v139
	global_store_dword v2, v142, s[52:53] offset:1024
	global_store_dword v2, v143, s[54:55]
	s_add_u32 s52, s52, 0x1800
	s_addc_u32 s53, s53, 0
	s_add_u32 s54, s54, 0x400
	s_addc_u32 s55, s55, 0
	v_add_f32_e32 v136, v106, v132
	v_add_f32_e32 v137, v107, v133
	v_add_f32_e32 v138, v122, v134
	v_add_f32_e32 v139, v123, v135
	v_mul_f32_e32 v136, 0xbfb8aa3b, v136
	v_mul_f32_e32 v137, 0xbfb8aa3b, v137
	v_mul_f32_e32 v138, 0xbfb8aa3b, v138
	v_mul_f32_e32 v139, 0xbfb8aa3b, v139
	v_exp_f32_e32 v136, v136
	v_exp_f32_e32 v137, v137
	v_exp_f32_e32 v138, v138
	v_exp_f32_e32 v139, v139
	v_lshlrev_b32_e32 v140, 16, v85
	v_and_b32_e32 v141, 0xffff0000, v85
	v_mul_f32_e32 v136, v140, v136
	v_mul_f32_e32 v137, v141, v137
	v_mul_f32_e32 v138, v140, v138
	v_mul_f32_e32 v139, v141, v139
	v_cvt_pk_bf16_f32 v142, v136, v137
	v_cvt_pk_bf16_f32 v143, v138, v139
	global_store_dword v2, v142, s[52:53] offset:1024
	global_store_dword v2, v143, s[54:55]
	s_add_u32 s52, s52, 0x1800
	s_addc_u32 s53, s53, 0
	s_add_u32 s54, s54, 0x400
	s_addc_u32 s55, s55, 0
	v_add_f32_e32 v136, v108, v132
	v_add_f32_e32 v137, v109, v133
	v_add_f32_e32 v138, v124, v134
	v_add_f32_e32 v139, v125, v135
	v_mul_f32_e32 v136, 0xbfb8aa3b, v136
	v_mul_f32_e32 v137, 0xbfb8aa3b, v137
	v_mul_f32_e32 v138, 0xbfb8aa3b, v138
	v_mul_f32_e32 v139, 0xbfb8aa3b, v139
	v_exp_f32_e32 v136, v136
	v_exp_f32_e32 v137, v137
	v_exp_f32_e32 v138, v138
	v_exp_f32_e32 v139, v139
	v_lshlrev_b32_e32 v140, 16, v86
	v_and_b32_e32 v141, 0xffff0000, v86
	v_mul_f32_e32 v136, v140, v136
	v_mul_f32_e32 v137, v141, v137
	v_mul_f32_e32 v138, v140, v138
	v_mul_f32_e32 v139, v141, v139
	v_cvt_pk_bf16_f32 v142, v136, v137
	v_cvt_pk_bf16_f32 v143, v138, v139
	global_store_dword v2, v142, s[52:53] offset:1024
	global_store_dword v2, v143, s[54:55]
	s_add_u32 s52, s52, 0x1800
	s_addc_u32 s53, s53, 0
	s_add_u32 s54, s54, 0x400
	s_addc_u32 s55, s55, 0
	v_add_f32_e32 v136, v110, v132
	v_add_f32_e32 v137, v111, v133
	v_add_f32_e32 v138, v126, v134
	v_add_f32_e32 v139, v127, v135
	v_mul_f32_e32 v136, 0xbfb8aa3b, v136
	v_mul_f32_e32 v137, 0xbfb8aa3b, v137
	v_mul_f32_e32 v138, 0xbfb8aa3b, v138
	v_mul_f32_e32 v139, 0xbfb8aa3b, v139
	v_exp_f32_e32 v136, v136
	v_exp_f32_e32 v137, v137
	v_exp_f32_e32 v138, v138
	v_exp_f32_e32 v139, v139
	v_lshlrev_b32_e32 v140, 16, v87
	v_and_b32_e32 v141, 0xffff0000, v87
	v_mul_f32_e32 v136, v140, v136
	v_mul_f32_e32 v137, v141, v137
	v_mul_f32_e32 v138, v140, v138
	v_mul_f32_e32 v139, v141, v139
	v_cvt_pk_bf16_f32 v142, v136, v137
	v_cvt_pk_bf16_f32 v143, v138, v139
	global_store_dword v2, v142, s[52:53] offset:1024
	global_store_dword v2, v143, s[54:55]
	s_cmp_lt_u32 s39, 4
	s_cbranch_scc1 .Lp7_noq_store
	s_mov_b64 s[52:53], s[42:43]
	s_mov_b64 s[54:55], s[44:45]
	v_add_f32_e32 v136, v96, v132
	v_add_f32_e32 v137, v97, v133
	v_add_f32_e32 v138, v112, v134
	v_add_f32_e32 v139, v113, v135
	v_mul_f32_e32 v136, 0x3fb8aa3b, v136
	v_mul_f32_e32 v137, 0x3fb8aa3b, v137
	v_mul_f32_e32 v138, 0x3fb8aa3b, v138
	v_mul_f32_e32 v139, 0x3fb8aa3b, v139
	v_exp_f32_e32 v136, v136
	v_exp_f32_e32 v137, v137
	v_exp_f32_e32 v138, v138
	v_exp_f32_e32 v139, v139
	v_lshlrev_b32_e32 v140, 16, v88
	v_and_b32_e32 v141, 0xffff0000, v88
	v_mul_f32_e32 v136, v140, v136
	v_mul_f32_e32 v137, v141, v137
	v_mul_f32_e32 v138, v140, v138
	v_mul_f32_e32 v139, v141, v139
	v_cvt_pk_bf16_f32 v142, v136, v137
	v_cvt_pk_bf16_f32 v143, v138, v139
	global_store_dword v2, v142, s[52:53]
	global_store_dword v2, v143, s[54:55]
	s_add_u32 s52, s52, 0x1800
	s_addc_u32 s53, s53, 0
	s_add_u32 s54, s54, 0x400
	s_addc_u32 s55, s55, 0
	v_add_f32_e32 v136, v98, v132
	v_add_f32_e32 v137, v99, v133
	v_add_f32_e32 v138, v114, v134
	v_add_f32_e32 v139, v115, v135
	v_mul_f32_e32 v136, 0x3fb8aa3b, v136
	v_mul_f32_e32 v137, 0x3fb8aa3b, v137
	v_mul_f32_e32 v138, 0x3fb8aa3b, v138
	v_mul_f32_e32 v139, 0x3fb8aa3b, v139
	v_exp_f32_e32 v136, v136
	v_exp_f32_e32 v137, v137
	v_exp_f32_e32 v138, v138
	v_exp_f32_e32 v139, v139
	v_lshlrev_b32_e32 v140, 16, v89
	v_and_b32_e32 v141, 0xffff0000, v89
	v_mul_f32_e32 v136, v140, v136
	v_mul_f32_e32 v137, v141, v137
	v_mul_f32_e32 v138, v140, v138
	v_mul_f32_e32 v139, v141, v139
	v_cvt_pk_bf16_f32 v142, v136, v137
	v_cvt_pk_bf16_f32 v143, v138, v139
	global_store_dword v2, v142, s[52:53]
	global_store_dword v2, v143, s[54:55]
	s_add_u32 s52, s52, 0x1800
	s_addc_u32 s53, s53, 0
	s_add_u32 s54, s54, 0x400
	s_addc_u32 s55, s55, 0
	v_add_f32_e32 v136, v100, v132
	v_add_f32_e32 v137, v101, v133
	v_add_f32_e32 v138, v116, v134
	v_add_f32_e32 v139, v117, v135
	v_mul_f32_e32 v136, 0x3fb8aa3b, v136
	v_mul_f32_e32 v137, 0x3fb8aa3b, v137
	v_mul_f32_e32 v138, 0x3fb8aa3b, v138
	v_mul_f32_e32 v139, 0x3fb8aa3b, v139
	v_exp_f32_e32 v136, v136
	v_exp_f32_e32 v137, v137
	v_exp_f32_e32 v138, v138
	v_exp_f32_e32 v139, v139
	v_lshlrev_b32_e32 v140, 16, v90
	v_and_b32_e32 v141, 0xffff0000, v90
	v_mul_f32_e32 v136, v140, v136
	v_mul_f32_e32 v137, v141, v137
	v_mul_f32_e32 v138, v140, v138
	v_mul_f32_e32 v139, v141, v139
	v_cvt_pk_bf16_f32 v142, v136, v137
	v_cvt_pk_bf16_f32 v143, v138, v139
	global_store_dword v2, v142, s[52:53]
	global_store_dword v2, v143, s[54:55]
	s_add_u32 s52, s52, 0x1800
	s_addc_u32 s53, s53, 0
	s_add_u32 s54, s54, 0x400
	s_addc_u32 s55, s55, 0
	v_add_f32_e32 v136, v102, v132
	v_add_f32_e32 v137, v103, v133
	v_add_f32_e32 v138, v118, v134
	v_add_f32_e32 v139, v119, v135
	v_mul_f32_e32 v136, 0x3fb8aa3b, v136
	v_mul_f32_e32 v137, 0x3fb8aa3b, v137
	v_mul_f32_e32 v138, 0x3fb8aa3b, v138
	v_mul_f32_e32 v139, 0x3fb8aa3b, v139
	v_exp_f32_e32 v136, v136
	v_exp_f32_e32 v137, v137
	v_exp_f32_e32 v138, v138
	v_exp_f32_e32 v139, v139
	v_lshlrev_b32_e32 v140, 16, v91
	v_and_b32_e32 v141, 0xffff0000, v91
	v_mul_f32_e32 v136, v140, v136
	v_mul_f32_e32 v137, v141, v137
	v_mul_f32_e32 v138, v140, v138
	v_mul_f32_e32 v139, v141, v139
	v_cvt_pk_bf16_f32 v142, v136, v137
	v_cvt_pk_bf16_f32 v143, v138, v139
	global_store_dword v2, v142, s[52:53]
	global_store_dword v2, v143, s[54:55]
	s_add_u32 s52, s52, 0x1800
	s_addc_u32 s53, s53, 0
	s_add_u32 s54, s54, 0x400
	s_addc_u32 s55, s55, 0
	v_add_f32_e32 v136, v104, v132
	v_add_f32_e32 v137, v105, v133
	v_add_f32_e32 v138, v120, v134
	v_add_f32_e32 v139, v121, v135
	v_mul_f32_e32 v136, 0x3fb8aa3b, v136
	v_mul_f32_e32 v137, 0x3fb8aa3b, v137
	v_mul_f32_e32 v138, 0x3fb8aa3b, v138
	v_mul_f32_e32 v139, 0x3fb8aa3b, v139
	v_exp_f32_e32 v136, v136
	v_exp_f32_e32 v137, v137
	v_exp_f32_e32 v138, v138
	v_exp_f32_e32 v139, v139
	v_lshlrev_b32_e32 v140, 16, v92
	v_and_b32_e32 v141, 0xffff0000, v92
	v_mul_f32_e32 v136, v140, v136
	v_mul_f32_e32 v137, v141, v137
	v_mul_f32_e32 v138, v140, v138
	v_mul_f32_e32 v139, v141, v139
	v_cvt_pk_bf16_f32 v142, v136, v137
	v_cvt_pk_bf16_f32 v143, v138, v139
	global_store_dword v2, v142, s[52:53]
	global_store_dword v2, v143, s[54:55]
	s_add_u32 s52, s52, 0x1800
	s_addc_u32 s53, s53, 0
	s_add_u32 s54, s54, 0x400
	s_addc_u32 s55, s55, 0
	v_add_f32_e32 v136, v106, v132
	v_add_f32_e32 v137, v107, v133
	v_add_f32_e32 v138, v122, v134
	v_add_f32_e32 v139, v123, v135
	v_mul_f32_e32 v136, 0x3fb8aa3b, v136
	v_mul_f32_e32 v137, 0x3fb8aa3b, v137
	v_mul_f32_e32 v138, 0x3fb8aa3b, v138
	v_mul_f32_e32 v139, 0x3fb8aa3b, v139
	v_exp_f32_e32 v136, v136
	v_exp_f32_e32 v137, v137
	v_exp_f32_e32 v138, v138
	v_exp_f32_e32 v139, v139
	v_lshlrev_b32_e32 v140, 16, v93
	v_and_b32_e32 v141, 0xffff0000, v93
	v_mul_f32_e32 v136, v140, v136
	v_mul_f32_e32 v137, v141, v137
	v_mul_f32_e32 v138, v140, v138
	v_mul_f32_e32 v139, v141, v139
	v_cvt_pk_bf16_f32 v142, v136, v137
	v_cvt_pk_bf16_f32 v143, v138, v139
	global_store_dword v2, v142, s[52:53]
	global_store_dword v2, v143, s[54:55]
	s_add_u32 s52, s52, 0x1800
	s_addc_u32 s53, s53, 0
	s_add_u32 s54, s54, 0x400
	s_addc_u32 s55, s55, 0
	v_add_f32_e32 v136, v108, v132
	v_add_f32_e32 v137, v109, v133
	v_add_f32_e32 v138, v124, v134
	v_add_f32_e32 v139, v125, v135
	v_mul_f32_e32 v136, 0x3fb8aa3b, v136
	v_mul_f32_e32 v137, 0x3fb8aa3b, v137
	v_mul_f32_e32 v138, 0x3fb8aa3b, v138
	v_mul_f32_e32 v139, 0x3fb8aa3b, v139
	v_exp_f32_e32 v136, v136
	v_exp_f32_e32 v137, v137
	v_exp_f32_e32 v138, v138
	v_exp_f32_e32 v139, v139
	v_lshlrev_b32_e32 v140, 16, v94
	v_and_b32_e32 v141, 0xffff0000, v94
	v_mul_f32_e32 v136, v140, v136
	v_mul_f32_e32 v137, v141, v137
	v_mul_f32_e32 v138, v140, v138
	v_mul_f32_e32 v139, v141, v139
	v_cvt_pk_bf16_f32 v142, v136, v137
	v_cvt_pk_bf16_f32 v143, v138, v139
	global_store_dword v2, v142, s[52:53]
	global_store_dword v2, v143, s[54:55]
	s_add_u32 s52, s52, 0x1800
	s_addc_u32 s53, s53, 0
	s_add_u32 s54, s54, 0x400
	s_addc_u32 s55, s55, 0
	v_add_f32_e32 v136, v110, v132
	v_add_f32_e32 v137, v111, v133
	v_add_f32_e32 v138, v126, v134
	v_add_f32_e32 v139, v127, v135
	v_mul_f32_e32 v136, 0x3fb8aa3b, v136
	v_mul_f32_e32 v137, 0x3fb8aa3b, v137
	v_mul_f32_e32 v138, 0x3fb8aa3b, v138
	v_mul_f32_e32 v139, 0x3fb8aa3b, v139
	v_exp_f32_e32 v136, v136
	v_exp_f32_e32 v137, v137
	v_exp_f32_e32 v138, v138
	v_exp_f32_e32 v139, v139
	v_lshlrev_b32_e32 v140, 16, v95
	v_and_b32_e32 v141, 0xffff0000, v95
	v_mul_f32_e32 v136, v140, v136
	v_mul_f32_e32 v137, v141, v137
	v_mul_f32_e32 v138, v140, v138
	v_mul_f32_e32 v139, v141, v139
	v_cvt_pk_bf16_f32 v142, v136, v137
	v_cvt_pk_bf16_f32 v143, v138, v139
	global_store_dword v2, v142, s[52:53]
	global_store_dword v2, v143, s[54:55]
.Lp7_noq_store:
	s_cmpk_lt_i32 s51, 0x480
	s_cbranch_scc0 .Lp7_exit
	s_mov_b32 s34, s51
	s_xor_b32 s50, s50, 1
	s_mov_b32 s38, s80
	s_mov_b32 s39, s81
	s_mov_b32 s40, s82
	s_mov_b32 s41, s83
	s_mov_b64 s[42:43], s[84:85]
	s_mov_b64 s[44:45], s[86:87]
	s_mov_b64 s[46:47], s[98:99]
	s_mov_b64 s[48:49], s[100:101]
	s_branch .Lp7_item
.Lp7_exit:
	v_readlane_b32 s69, v251, 49
	s_nop 3
